# grid barriers: acquire invalidate issued at arrival instead of after the release is seen (9 barriers) and before the panel-counter wait in the fused final norm; P4 v2 unchanged
# speedup vs baseline: 1.1101x; 1.0163x over previous
; __device__ __forceinline__ unsigned xb_ld(unsigned* p)              { return __hip_atomic_load(p, __ATOMIC_RELAXED, __HIP_MEMORY_SCOPE_AGENT); }
; __device__ __forceinline__ unsigned xb_add(unsigned* p, unsigned v) { return __hip_atomic_fetch_add(p, v, __ATOMIC_RELAXED, __HIP_MEMORY_SCOPE_AGENT); }
; #define XB_SPIN(cond, bar) do { unsigned _sp = 0; while (cond) { __builtin_amdgcn_s_sleep(1); \
;     if ((++_sp & 255u) == 0u) { if (xb_ld(&(bar)[XB_TMO])) break; if (_sp > XB_SPIN_CAP) { atomicAdd(&(bar)[XB_TMO], 1u); break; } } } } while (0)
; __device__ __forceinline__ void xcd_barrier(const XcdBarrier& b) {
;     ...
;     if (threadIdx.x == 0) {
;         unsigned* bar = b.bar;
;         __builtin_amdgcn_s_waitcnt(0);
;         unsigned nloc = b.st[0], nx = b.st[1];
;         if (nloc == 0u) { xcd_barrier_complete(bar, b.x, nloc, nx); b.st[0] = nloc; b.st[1] = nx; }
;         const unsigned old = xb_add(&bar[XB_XSUB(b.x)], 1u);
;         const unsigned gen = old / nloc;
;         if (old + 1u == (gen + 1u) * nloc) {
;             __builtin_amdgcn_fence(__ATOMIC_RELEASE, "agent");
;             asm volatile("s_waitcnt vmcnt(0)" ::: "memory");
;             const unsigned og = xb_add(&bar[XB_TOP], 1u);
;             const unsigned tg = og / nx;
;             if (og + 1u == (tg + 1u) * nx) xb_add(&bar[XB_TOPGEN], 1u);
;             else XB_SPIN(xb_ld(&bar[XB_TOPGEN]) == tg, bar);
.LBB0_70:
	s_or_b64 exec, exec, s[10:11]
	v_cvt_f32_u32_e32 v4, v2
	s_waitcnt vmcnt(0)
	buffer_inv sc1
	v_readfirstlane_b32 s0, v3
	v_sub_u32_e32 v3, 0, v2
	v_rcp_iflag_f32_e32 v4, v4
	v_add_u32_e32 v5, s0, v1
	v_mul_f32_e32 v4, 0x4f7ffffe, v4
	v_cvt_u32_f32_e32 v4, v4
	v_mul_lo_u32 v1, v3, v4
	v_mul_hi_u32 v1, v4, v1
	v_add_u32_e32 v1, v4, v1
	v_mul_hi_u32 v1, v5, v1
	v_mul_lo_u32 v3, v1, v2
	v_sub_u32_e32 v3, v5, v3
	v_add_u32_e32 v4, 1, v1
	v_cmp_ge_u32_e32 vcc, v3, v2
	s_nop 1
	v_cndmask_b32_e32 v1, v1, v4, vcc
	v_sub_u32_e32 v4, v3, v2
	v_cndmask_b32_e32 v3, v3, v4, vcc
	v_add_u32_e32 v4, 1, v1
	v_cmp_ge_u32_e32 vcc, v3, v2
	v_add_u32_e32 v3, 1, v5
	s_nop 0
	v_cndmask_b32_e32 v1, v1, v4, vcc
	v_mul_lo_u32 v4, v2, v1
	v_add_u32_e32 v2, v4, v2
	v_cmp_ne_u32_e32 vcc, v3, v2
	s_and_saveexec_b64 s[0:1], vcc
	s_xor_b64 s[10:11], exec, s[0:1]
	s_cbranch_execz .LBB0_84
	s_waitcnt lgkmcnt(0)
	v_mov_b32_e32 v0, 0x2000
	global_load_dword v0, v0, s[8:9] offset:1024 sc1
	s_add_u32 s14, s8, 0x2400
	s_addc_u32 s15, s9, 0
	s_waitcnt vmcnt(0)
	v_cmp_eq_u32_e32 vcc, v0, v1
	s_and_saveexec_b64 s[4:5], vcc
	s_cbranch_execz .LBB0_83
	s_add_u32 s12, s90, 0x10bd2a00
	s_addc_u32 s13, s91, 0
	s_mov_b32 s0, 1
	s_mov_b64 s[16:17], 0
	v_mov_b32_e32 v0, 0
	s_branch .LBB0_74

; __device__ __forceinline__ unsigned xb_ld(unsigned* p)              { return __hip_atomic_load(p, __ATOMIC_RELAXED, __HIP_MEMORY_SCOPE_AGENT); }
; #define XB_SPIN(cond, bar) do { unsigned _sp = 0; while (cond) { __builtin_amdgcn_s_sleep(1); \
;     if ((++_sp & 255u) == 0u) { if (xb_ld(&(bar)[XB_TMO])) break; if (_sp > XB_SPIN_CAP) { atomicAdd(&(bar)[XB_TMO], 1u); break; } } } } while (0)
; __device__ __forceinline__ void xcd_barrier(const XcdBarrier& b) {
;     ...
;         } else {
;             XB_SPIN(xb_ld(&bar[XB_XGEN(b.x)]) == gen, bar);
;             __builtin_amdgcn_fence(__ATOMIC_ACQUIRE, "agent");
;             asm volatile("s_waitcnt vmcnt(0)" ::: "memory");
;         }
.LBB0_83:
	s_or_b64 exec, exec, s[4:5]
	s_waitcnt vmcnt(0)
	s_waitcnt vmcnt(0)

; __device__ __forceinline__ unsigned xb_ld(unsigned* p)              { return __hip_atomic_load(p, __ATOMIC_RELAXED, __HIP_MEMORY_SCOPE_AGENT); }
; __device__ __forceinline__ unsigned xb_add(unsigned* p, unsigned v) { return __hip_atomic_fetch_add(p, v, __ATOMIC_RELAXED, __HIP_MEMORY_SCOPE_AGENT); }
; #define XB_SPIN(cond, bar) do { unsigned _sp = 0; while (cond) { __builtin_amdgcn_s_sleep(1); \
;     if ((++_sp & 255u) == 0u) { if (xb_ld(&(bar)[XB_TMO])) break; if (_sp > XB_SPIN_CAP) { atomicAdd(&(bar)[XB_TMO], 1u); break; } } } } while (0)
; __device__ __forceinline__ void xcd_barrier(const XcdBarrier& b) {
;     ...
;             const unsigned og = xb_add(&bar[XB_TOP], 1u);
;             const unsigned tg = og / nx;
;             if (og + 1u == (tg + 1u) * nx) xb_add(&bar[XB_TOPGEN], 1u);
;             else XB_SPIN(xb_ld(&bar[XB_TOPGEN]) == tg, bar);
;             __builtin_amdgcn_fence(__ATOMIC_ACQUIRE, "agent");
;             xb_add(&bar[XB_XGEN(b.x)], 1u);
.LBB0_101:
	s_or_b64 exec, exec, s[4:5]
	s_mov_b64 s[4:5], exec
	v_mbcnt_lo_u32_b32 v0, s4, 0
	v_mbcnt_hi_u32_b32 v0, s5, v0
	v_cmp_eq_u32_e32 vcc, 0, v0
	s_waitcnt vmcnt(0)
	s_and_saveexec_b64 s[10:11], vcc
	s_cbranch_execz .LBB0_103
	s_bcnt1_i32_b64 s0, s[4:5]
	v_mov_b32_e32 v0, 0x2000
	v_mov_b32_e32 v1, s0
	global_atomic_add v0, v1, s[8:9] offset:1024

; __device__ __forceinline__ unsigned xb_ld(unsigned* p)              { return __hip_atomic_load(p, __ATOMIC_RELAXED, __HIP_MEMORY_SCOPE_AGENT); }
; __device__ __forceinline__ unsigned xb_add(unsigned* p, unsigned v) { return __hip_atomic_fetch_add(p, v, __ATOMIC_RELAXED, __HIP_MEMORY_SCOPE_AGENT); }
; #define XB_SPIN(cond, bar) do { unsigned _sp = 0; while (cond) { __builtin_amdgcn_s_sleep(1); \
;     if ((++_sp & 255u) == 0u) { if (xb_ld(&(bar)[XB_TMO])) break; if (_sp > XB_SPIN_CAP) { atomicAdd(&(bar)[XB_TMO], 1u); break; } } } } while (0)
; __device__ __forceinline__ void xcd_barrier(const XcdBarrier& b) {
;     ...
;     if (threadIdx.x == 0) {
;         unsigned* bar = b.bar;
;         __builtin_amdgcn_s_waitcnt(0);
;         unsigned nloc = b.st[0], nx = b.st[1];
;         if (nloc == 0u) { xcd_barrier_complete(bar, b.x, nloc, nx); b.st[0] = nloc; b.st[1] = nx; }
;         const unsigned old = xb_add(&bar[XB_XSUB(b.x)], 1u);
;         const unsigned gen = old / nloc;
;         if (old + 1u == (gen + 1u) * nloc) {
;             __builtin_amdgcn_fence(__ATOMIC_RELEASE, "agent");
;             asm volatile("s_waitcnt vmcnt(0)" ::: "memory");
;             const unsigned og = xb_add(&bar[XB_TOP], 1u);
;             const unsigned tg = og / nx;
;             if (og + 1u == (tg + 1u) * nx) xb_add(&bar[XB_TOPGEN], 1u);
;             else XB_SPIN(xb_ld(&bar[XB_TOPGEN]) == tg, bar);
.LBB0_634:
	s_or_b64 exec, exec, s[8:9]
	v_cvt_f32_u32_e32 v4, v2
	s_waitcnt vmcnt(0)
	buffer_inv sc1
	v_readfirstlane_b32 s4, v3
	v_sub_u32_e32 v3, 0, v2
	v_rcp_iflag_f32_e32 v4, v4
	v_add_u32_e32 v5, s4, v1
	v_mul_f32_e32 v4, 0x4f7ffffe, v4
	v_cvt_u32_f32_e32 v4, v4
	v_mul_lo_u32 v1, v3, v4
	v_mul_hi_u32 v1, v4, v1
	v_add_u32_e32 v1, v4, v1
	v_mul_hi_u32 v1, v5, v1
	v_mul_lo_u32 v3, v1, v2
	v_sub_u32_e32 v3, v5, v3
	v_add_u32_e32 v4, 1, v1
	v_cmp_ge_u32_e32 vcc, v3, v2
	s_nop 1
	v_cndmask_b32_e32 v1, v1, v4, vcc
	v_sub_u32_e32 v4, v3, v2
	v_cndmask_b32_e32 v3, v3, v4, vcc
	v_add_u32_e32 v4, 1, v1
	v_cmp_ge_u32_e32 vcc, v3, v2
	v_add_u32_e32 v3, 1, v5
	s_nop 0
	v_cndmask_b32_e32 v1, v1, v4, vcc
	v_mul_lo_u32 v4, v2, v1
	v_add_u32_e32 v2, v4, v2
	v_cmp_ne_u32_e32 vcc, v3, v2
	s_and_saveexec_b64 s[4:5], vcc
	s_xor_b64 s[8:9], exec, s[4:5]
	s_cbranch_execz .LBB0_648
	s_waitcnt lgkmcnt(0)
	v_mov_b32_e32 v0, 0x2000
	global_load_dword v0, v0, s[6:7] offset:1024 sc1
	s_add_u32 s20, s6, 0x2400
	s_addc_u32 s21, s7, 0
	s_waitcnt vmcnt(0)
	v_cmp_eq_u32_e32 vcc, v0, v1
	s_and_saveexec_b64 s[4:5], vcc
	s_cbranch_execz .LBB0_647
	s_add_u32 s14, s90, 0x10bd2a00
	s_addc_u32 s15, s91, 0
	s_mov_b32 s10, 1
	s_mov_b64 s[24:25], 0
	v_mov_b32_e32 v0, 0
	s_branch .LBB0_638

; __device__ __forceinline__ unsigned xb_ld(unsigned* p)              { return __hip_atomic_load(p, __ATOMIC_RELAXED, __HIP_MEMORY_SCOPE_AGENT); }
; __device__ __forceinline__ unsigned xb_add(unsigned* p, unsigned v) { return __hip_atomic_fetch_add(p, v, __ATOMIC_RELAXED, __HIP_MEMORY_SCOPE_AGENT); }
; #define XB_SPIN(cond, bar) do { unsigned _sp = 0; while (cond) { __builtin_amdgcn_s_sleep(1); \
;     if ((++_sp & 255u) == 0u) { if (xb_ld(&(bar)[XB_TMO])) break; if (_sp > XB_SPIN_CAP) { atomicAdd(&(bar)[XB_TMO], 1u); break; } } } } while (0)
; __device__ __forceinline__ void xcd_barrier(const XcdBarrier& b) {
;     ...
;             const unsigned og = xb_add(&bar[XB_TOP], 1u);
;             const unsigned tg = og / nx;
;             if (og + 1u == (tg + 1u) * nx) xb_add(&bar[XB_TOPGEN], 1u);
;             else XB_SPIN(xb_ld(&bar[XB_TOPGEN]) == tg, bar);
;             __builtin_amdgcn_fence(__ATOMIC_ACQUIRE, "agent");
;             xb_add(&bar[XB_XGEN(b.x)], 1u);
.LBB0_665:
	s_or_b64 exec, exec, s[4:5]
	s_mov_b64 s[4:5], exec
	v_mbcnt_lo_u32_b32 v0, s4, 0
	v_mbcnt_hi_u32_b32 v0, s5, v0
	v_cmp_eq_u32_e32 vcc, 0, v0
	s_waitcnt vmcnt(0)
	s_and_saveexec_b64 s[8:9], vcc
	s_cbranch_execz .LBB0_667
	s_bcnt1_i32_b64 s4, s[4:5]
	v_mov_b32_e32 v0, 0x2000
	v_mov_b32_e32 v1, s4
	global_atomic_add v0, v1, s[6:7] offset:1024

; __device__ __forceinline__ unsigned xb_ld(unsigned* p)              { return __hip_atomic_load(p, __ATOMIC_RELAXED, __HIP_MEMORY_SCOPE_AGENT); }
; __device__ __forceinline__ unsigned xb_add(unsigned* p, unsigned v) { return __hip_atomic_fetch_add(p, v, __ATOMIC_RELAXED, __HIP_MEMORY_SCOPE_AGENT); }
; #define XB_SPIN(cond, bar) do { unsigned _sp = 0; while (cond) { __builtin_amdgcn_s_sleep(1); \
;     if ((++_sp & 255u) == 0u) { if (xb_ld(&(bar)[XB_TMO])) break; if (_sp > XB_SPIN_CAP) { atomicAdd(&(bar)[XB_TMO], 1u); break; } } } } while (0)
; __device__ __forceinline__ void xcd_barrier(const XcdBarrier& b) {
;     ...
;     if (threadIdx.x == 0) {
;         unsigned* bar = b.bar;
;         __builtin_amdgcn_s_waitcnt(0);
;         unsigned nloc = b.st[0], nx = b.st[1];
;         if (nloc == 0u) { xcd_barrier_complete(bar, b.x, nloc, nx); b.st[0] = nloc; b.st[1] = nx; }
;         const unsigned old = xb_add(&bar[XB_XSUB(b.x)], 1u);
;         const unsigned gen = old / nloc;
;         if (old + 1u == (gen + 1u) * nloc) {
;             __builtin_amdgcn_fence(__ATOMIC_RELEASE, "agent");
;             asm volatile("s_waitcnt vmcnt(0)" ::: "memory");
;             const unsigned og = xb_add(&bar[XB_TOP], 1u);
;             const unsigned tg = og / nx;
;             if (og + 1u == (tg + 1u) * nx) xb_add(&bar[XB_TOPGEN], 1u);
;             else XB_SPIN(xb_ld(&bar[XB_TOPGEN]) == tg, bar);
.LBB0_910:
	s_or_b64 exec, exec, s[8:9]
	v_cvt_f32_u32_e32 v4, v2
	s_waitcnt vmcnt(0)
	buffer_inv sc1
	v_readfirstlane_b32 s4, v3
	v_sub_u32_e32 v3, 0, v2
	v_rcp_iflag_f32_e32 v4, v4
	v_add_u32_e32 v5, s4, v1
	v_mul_f32_e32 v4, 0x4f7ffffe, v4
	v_cvt_u32_f32_e32 v4, v4
	v_mul_lo_u32 v1, v3, v4
	v_mul_hi_u32 v1, v4, v1
	v_add_u32_e32 v1, v4, v1
	v_mul_hi_u32 v1, v5, v1
	v_mul_lo_u32 v3, v1, v2
	v_sub_u32_e32 v3, v5, v3
	v_add_u32_e32 v4, 1, v1
	v_cmp_ge_u32_e32 vcc, v3, v2
	s_nop 1
	v_cndmask_b32_e32 v1, v1, v4, vcc
	v_sub_u32_e32 v4, v3, v2
	v_cndmask_b32_e32 v3, v3, v4, vcc
	v_add_u32_e32 v4, 1, v1
	v_cmp_ge_u32_e32 vcc, v3, v2
	v_add_u32_e32 v3, 1, v5
	s_nop 0
	v_cndmask_b32_e32 v1, v1, v4, vcc
	v_mul_lo_u32 v4, v2, v1
	v_add_u32_e32 v2, v4, v2
	v_cmp_ne_u32_e32 vcc, v3, v2
	s_and_saveexec_b64 s[4:5], vcc
	s_xor_b64 s[8:9], exec, s[4:5]
	s_cbranch_execz .LBB0_924
	s_waitcnt lgkmcnt(0)
	v_mov_b32_e32 v0, 0x2000
	global_load_dword v0, v0, s[6:7] offset:1024 sc1
	s_add_u32 s30, s6, 0x2400
	s_addc_u32 s31, s7, 0
	s_waitcnt vmcnt(0)
	v_cmp_eq_u32_e32 vcc, v0, v1
	s_and_saveexec_b64 s[4:5], vcc
	s_cbranch_execz .LBB0_923
	s_add_u32 s12, s90, 0x10bd2a00
	s_addc_u32 s13, s91, 0
	s_mov_b32 s10, 1
	s_mov_b64 s[40:41], 0
	v_mov_b32_e32 v0, 0
	s_branch .LBB0_914

; __device__ __forceinline__ unsigned xb_ld(unsigned* p)              { return __hip_atomic_load(p, __ATOMIC_RELAXED, __HIP_MEMORY_SCOPE_AGENT); }
; __device__ __forceinline__ unsigned xb_add(unsigned* p, unsigned v) { return __hip_atomic_fetch_add(p, v, __ATOMIC_RELAXED, __HIP_MEMORY_SCOPE_AGENT); }
; #define XB_SPIN(cond, bar) do { unsigned _sp = 0; while (cond) { __builtin_amdgcn_s_sleep(1); \
;     if ((++_sp & 255u) == 0u) { if (xb_ld(&(bar)[XB_TMO])) break; if (_sp > XB_SPIN_CAP) { atomicAdd(&(bar)[XB_TMO], 1u); break; } } } } while (0)
; __device__ __forceinline__ void xcd_barrier(const XcdBarrier& b) {
;     ...
;     if (threadIdx.x == 0) {
;         unsigned* bar = b.bar;
;         __builtin_amdgcn_s_waitcnt(0);
;         unsigned nloc = b.st[0], nx = b.st[1];
;         if (nloc == 0u) { xcd_barrier_complete(bar, b.x, nloc, nx); b.st[0] = nloc; b.st[1] = nx; }
;         const unsigned old = xb_add(&bar[XB_XSUB(b.x)], 1u);
;         const unsigned gen = old / nloc;
;         if (old + 1u == (gen + 1u) * nloc) {
;             __builtin_amdgcn_fence(__ATOMIC_RELEASE, "agent");
;             asm volatile("s_waitcnt vmcnt(0)" ::: "memory");
;             const unsigned og = xb_add(&bar[XB_TOP], 1u);
;             const unsigned tg = og / nx;
;             if (og + 1u == (tg + 1u) * nx) xb_add(&bar[XB_TOPGEN], 1u);
;             else XB_SPIN(xb_ld(&bar[XB_TOPGEN]) == tg, bar);
.LBB0_989:
	s_or_b64 exec, exec, s[8:9]
	v_cvt_f32_u32_e32 v4, v2
	s_waitcnt vmcnt(0)
	buffer_inv sc1
	v_readfirstlane_b32 s4, v3
	v_sub_u32_e32 v3, 0, v2
	v_rcp_iflag_f32_e32 v4, v4
	v_add_u32_e32 v5, s4, v1
	v_mul_f32_e32 v4, 0x4f7ffffe, v4
	v_cvt_u32_f32_e32 v4, v4
	v_mul_lo_u32 v1, v3, v4
	v_mul_hi_u32 v1, v4, v1
	v_add_u32_e32 v1, v4, v1
	v_mul_hi_u32 v1, v5, v1
	v_mul_lo_u32 v3, v1, v2
	v_sub_u32_e32 v3, v5, v3
	v_add_u32_e32 v4, 1, v1
	v_cmp_ge_u32_e32 vcc, v3, v2
	s_nop 1
	v_cndmask_b32_e32 v1, v1, v4, vcc
	v_sub_u32_e32 v4, v3, v2
	v_cndmask_b32_e32 v3, v3, v4, vcc
	v_add_u32_e32 v4, 1, v1
	v_cmp_ge_u32_e32 vcc, v3, v2
	v_add_u32_e32 v3, 1, v5
	s_nop 0
	v_cndmask_b32_e32 v1, v1, v4, vcc
	v_mul_lo_u32 v4, v2, v1
	v_add_u32_e32 v2, v4, v2
	v_cmp_ne_u32_e32 vcc, v3, v2
	s_and_saveexec_b64 s[4:5], vcc
	s_xor_b64 s[8:9], exec, s[4:5]
	s_cbranch_execz .LBB0_1003
	s_waitcnt lgkmcnt(0)
	v_mov_b32_e32 v0, 0x2000
	global_load_dword v0, v0, s[6:7] offset:1024 sc1
	s_add_u32 s12, s6, 0x2400
	s_addc_u32 s13, s7, 0
	s_waitcnt vmcnt(0)
	v_cmp_eq_u32_e32 vcc, v0, v1
	s_and_saveexec_b64 s[4:5], vcc
	s_cbranch_execz .LBB0_1002
	s_add_u32 s10, s90, 0x10bd2a00
	s_addc_u32 s11, s91, 0
	s_mov_b32 s14, 1
	s_mov_b64 s[26:27], 0
	v_mov_b32_e32 v0, 0
	s_branch .LBB0_993

; __device__ __forceinline__ unsigned xb_ld(unsigned* p)              { return __hip_atomic_load(p, __ATOMIC_RELAXED, __HIP_MEMORY_SCOPE_AGENT); }
; __device__ __forceinline__ unsigned xb_add(unsigned* p, unsigned v) { return __hip_atomic_fetch_add(p, v, __ATOMIC_RELAXED, __HIP_MEMORY_SCOPE_AGENT); }
; #define XB_SPIN(cond, bar) do { unsigned _sp = 0; while (cond) { __builtin_amdgcn_s_sleep(1); \
;     if ((++_sp & 255u) == 0u) { if (xb_ld(&(bar)[XB_TMO])) break; if (_sp > XB_SPIN_CAP) { atomicAdd(&(bar)[XB_TMO], 1u); break; } } } } while (0)
; __device__ __forceinline__ void xcd_barrier(const XcdBarrier& b) {
;     ...
;     if (threadIdx.x == 0) {
;         unsigned* bar = b.bar;
;         __builtin_amdgcn_s_waitcnt(0);
;         unsigned nloc = b.st[0], nx = b.st[1];
;         if (nloc == 0u) { xcd_barrier_complete(bar, b.x, nloc, nx); b.st[0] = nloc; b.st[1] = nx; }
;         const unsigned old = xb_add(&bar[XB_XSUB(b.x)], 1u);
;         const unsigned gen = old / nloc;
;         if (old + 1u == (gen + 1u) * nloc) {
;             __builtin_amdgcn_fence(__ATOMIC_RELEASE, "agent");
;             asm volatile("s_waitcnt vmcnt(0)" ::: "memory");
;             const unsigned og = xb_add(&bar[XB_TOP], 1u);
;             const unsigned tg = og / nx;
;             if (og + 1u == (tg + 1u) * nx) xb_add(&bar[XB_TOPGEN], 1u);
;             else XB_SPIN(xb_ld(&bar[XB_TOPGEN]) == tg, bar);
.LBB0_1158:
	s_or_b64 exec, exec, s[8:9]
	v_cvt_f32_u32_e32 v4, v2
	s_waitcnt vmcnt(0)
	buffer_inv sc1
	v_readfirstlane_b32 s4, v3
	v_sub_u32_e32 v3, 0, v2
	v_rcp_iflag_f32_e32 v4, v4
	v_add_u32_e32 v5, s4, v1
	v_mul_f32_e32 v4, 0x4f7ffffe, v4
	v_cvt_u32_f32_e32 v4, v4
	v_mul_lo_u32 v1, v3, v4
	v_mul_hi_u32 v1, v4, v1
	v_add_u32_e32 v1, v4, v1
	v_mul_hi_u32 v1, v5, v1
	v_mul_lo_u32 v3, v1, v2
	v_sub_u32_e32 v3, v5, v3
	v_add_u32_e32 v4, 1, v1
	v_cmp_ge_u32_e32 vcc, v3, v2
	s_nop 1
	v_cndmask_b32_e32 v1, v1, v4, vcc
	v_sub_u32_e32 v4, v3, v2
	v_cndmask_b32_e32 v3, v3, v4, vcc
	v_add_u32_e32 v4, 1, v1
	v_cmp_ge_u32_e32 vcc, v3, v2
	v_add_u32_e32 v3, 1, v5
	s_nop 0
	v_cndmask_b32_e32 v1, v1, v4, vcc
	v_mul_lo_u32 v4, v2, v1
	v_add_u32_e32 v2, v4, v2
	v_cmp_ne_u32_e32 vcc, v3, v2
	s_and_saveexec_b64 s[4:5], vcc
	s_xor_b64 s[8:9], exec, s[4:5]
	s_cbranch_execz .LBB0_1172
	s_waitcnt lgkmcnt(0)
	v_mov_b32_e32 v0, 0x2000
	global_load_dword v0, v0, s[6:7] offset:1024 sc1
	s_add_u32 s12, s6, 0x2400
	s_addc_u32 s13, s7, 0
	s_waitcnt vmcnt(0)
	v_cmp_eq_u32_e32 vcc, v0, v1
	s_and_saveexec_b64 s[4:5], vcc
	s_cbranch_execz .LBB0_1171
	s_add_u32 s10, s90, 0x10bd2a00
	s_addc_u32 s11, s91, 0
	s_mov_b32 s14, 1
	s_mov_b64 s[16:17], 0
	v_mov_b32_e32 v0, 0
	s_branch .LBB0_1162

;     __device__ __forceinline__ void operator()(f32x4 (&acc)[2][2][4][2], const Unit& u, int wr, int wc, int fr, int fq) const {
;     ...
;         unsigned* pc = cnt + 64 * u.pm;
;         if ((threadIdx.x & 63) == 0) __hip_atomic_fetch_add(pc, 1u, __ATOMIC_RELAXED, __HIP_MEMORY_SCOPE_AGENT);
;         f32x4 gg[2][2];
; #pragma unroll
;         for (int bj = 0; bj < 2; ++bj)
; #pragma unroll
;             for (int n = 0; n < 2; ++n) gg[bj][n] = *(const f32x4*)(g + col0 + bj * 128 + n * 16);
;         { unsigned spins = 0; while (__hip_atomic_load(pc, __ATOMIC_RELAXED, __HIP_MEMORY_SCOPE_AGENT) < 64u) { __builtin_amdgcn_s_sleep(2); if (++spins > (1u << 22)) break; } }
;         __builtin_amdgcn_fence(__ATOMIC_ACQUIRE, "agent");
;         asm volatile("s_waitcnt vmcnt(0)" ::: "memory");
.LBB0_1341:
	s_or_b64 exec, exec, s[4:5]
	buffer_inv sc1
	s_waitcnt lgkmcnt(0)
	v_lshl_add_u64 v[0:1], v[144:145], 2, s[86:87]
	global_load_dwordx4 v[12:15], v[0:1], off
	global_load_dwordx4 v[8:11], v[0:1], off offset:64
	global_load_dwordx4 v[4:7], v[0:1], off offset:512
	s_nop 0
	global_load_dwordx4 v[0:3], v[0:1], off offset:576
	s_mov_b32 s6, 0x400001
	v_mov_b32_e32 v38, 0
	s_branch .LBB0_1343

;     __device__ __forceinline__ void operator()(f32x4 (&acc)[2][2][4][2], const Unit& u, int wr, int wc, int fr, int fq) const {
;     ...
;         { unsigned spins = 0; while (__hip_atomic_load(pc, __ATOMIC_RELAXED, __HIP_MEMORY_SCOPE_AGENT) < 64u) { __builtin_amdgcn_s_sleep(2); if (++spins > (1u << 22)) break; } }
;         __builtin_amdgcn_fence(__ATOMIC_ACQUIRE, "agent");
;         asm volatile("s_waitcnt vmcnt(0)" ::: "memory");
;         float rs[2][4];
; #pragma unroll
;         for (int ai = 0; ai < 2; ++ai)
; #pragma unroll
;             for (int m = 0; m < 4; ++m) rs[ai][m] = __hip_atomic_load(rowsq + row0 + ai * 128 + m * 16, __ATOMIC_RELAXED, __HIP_MEMORY_SCOPE_AGENT);
; #pragma unroll
;         for (int ai = 0; ai < 2; ++ai)
; #pragma unroll
;             for (int m = 0; m < 4; ++m) {
;                 const int row = row0 + ai * 128 + m * 16;
;                 const float rstd = rsqrtf(rs[ai][m] * (1.0f / D) + RMS_EPS);
; #pragma unroll
;                 for (int bj = 0; bj < 2; ++bj)
; #pragma unroll
;                     for (int n = 0; n < 2; ++n) { const int c = col0 + bj * 128 + n * 16; *(f32x4*)(out + (size_t)row * D + c) = acc[ai][bj][m][n] * rstd * gg[bj][n]; }
.LBB0_1349:
	s_waitcnt vmcnt(0)
	global_load_dword v53, v[174:175], off sc1
	global_load_dword v52, v[174:175], off offset:64 sc1
	global_load_dword v55, v[174:175], off offset:128 sc1
	global_load_dword v54, v[174:175], off offset:192 sc1
	global_load_dword v51, v[174:175], off offset:512 sc1
	global_load_dword v50, v[174:175], off offset:576 sc1
	global_load_dword v39, v[174:175], off offset:640 sc1
	global_load_dword v38, v[174:175], off offset:704 sc1
	s_mov_b32 s0, 0x358637bd
	s_mov_b32 s8, 0x3a000000
	v_mov_b64_e32 v[42:43], s[0:1]
	s_mov_b32 s4, 0x800000
	s_waitcnt vmcnt(6)
	v_pk_fma_f32 v[52:53], v[52:53], s[8:9], v[42:43] op_sel_hi:[1,0,0]
	s_nop 0
	v_cmp_gt_f32_e32 vcc, s4, v53
	s_waitcnt vmcnt(4)
	v_pk_fma_f32 v[62:63], v[54:55], s[8:9], v[42:43] op_sel_hi:[1,0,0]
	v_mul_f32_e32 v54, 0x4b800000, v53
	v_mul_f32_e32 v55, 0x4b800000, v52
	v_mul_f32_e32 v56, 0x4b800000, v63
	v_cndmask_b32_e32 v53, v53, v54, vcc
	v_cmp_gt_f32_e64 s[0:1], s4, v52
	v_cmp_gt_f32_e64 s[6:7], s4, v63
	v_rsq_f32_e32 v53, v53
	v_cndmask_b32_e64 v52, v52, v55, s[0:1]
	v_cndmask_b32_e64 v54, v63, v56, s[6:7]
	v_rsq_f32_e32 v55, v52
	v_rsq_f32_e32 v56, v54
	v_mul_f32_e32 v52, 0x45800000, v53
	v_cndmask_b32_e32 v52, v53, v52, vcc
	v_mul_f32_e32 v54, 0x45800000, v55
	v_mul_f32_e32 v57, 0x45800000, v56
	v_cndmask_b32_e64 v54, v55, v54, s[0:1]
	v_cndmask_b32_e64 v56, v56, v57, s[6:7]
	v_pk_mul_f32 v[58:59], v[154:155], v[52:53] op_sel_hi:[1,0]
	v_pk_mul_f32 v[152:153], v[152:153], v[52:53] op_sel_hi:[1,0]
	v_mul_f32_e32 v63, 0x4b800000, v62
	v_pk_mul_f32 v[154:155], v[158:159], v[52:53] op_sel_hi:[1,0]
	v_pk_mul_f32 v[156:157], v[156:157], v[52:53] op_sel_hi:[1,0]
	v_pk_mul_f32 v[158:159], v[162:163], v[52:53] op_sel_hi:[1,0]
	v_pk_mul_f32 v[160:161], v[160:161], v[52:53] op_sel_hi:[1,0]
	v_pk_mul_f32 v[162:163], v[166:167], v[52:53] op_sel_hi:[1,0]
	v_pk_mul_f32 v[164:165], v[164:165], v[52:53] op_sel_hi:[1,0]
	v_pk_mul_f32 v[140:141], v[140:141], v[54:55] op_sel_hi:[1,0]
	v_pk_mul_f32 v[142:143], v[142:143], v[54:55] op_sel_hi:[1,0]
	v_pk_mul_f32 v[136:137], v[136:137], v[54:55] op_sel_hi:[1,0]
	v_pk_mul_f32 v[138:139], v[138:139], v[54:55] op_sel_hi:[1,0]
	v_pk_mul_f32 v[166:167], v[132:133], v[54:55] op_sel_hi:[1,0]
	v_pk_mul_f32 v[134:135], v[134:135], v[54:55] op_sel_hi:[1,0]
	v_pk_mul_f32 v[170:171], v[170:171], v[54:55] op_sel_hi:[1,0]
	v_pk_mul_f32 v[174:175], v[130:131], v[54:55] op_sel_hi:[1,0]
	v_pk_mul_f32 v[176:177], v[124:125], v[56:57] op_sel_hi:[1,0]
	v_pk_mul_f32 v[126:127], v[126:127], v[56:57] op_sel_hi:[1,0]
	v_pk_mul_f32 v[178:179], v[120:121], v[56:57] op_sel_hi:[1,0]
	v_pk_mul_f32 v[190:191], v[122:123], v[56:57] op_sel_hi:[1,0]
	v_pk_mul_f32 v[192:193], v[116:117], v[56:57] op_sel_hi:[1,0]
	v_pk_mul_f32 v[194:195], v[118:119], v[56:57] op_sel_hi:[1,0]
	v_pk_mul_f32 v[54:55], v[14:15], v[152:153]
	v_pk_mul_f32 v[52:53], v[12:13], v[58:59]
	v_cmp_gt_f32_e32 vcc, s4, v62
	v_pk_mul_f32 v[172:173], v[172:173], v[56:57] op_sel_hi:[1,0]
	v_pk_mul_f32 v[198:199], v[114:115], v[56:57] op_sel_hi:[1,0]
	v_pk_mul_f32 v[58:59], v[10:11], v[156:157]
	v_pk_mul_f32 v[56:57], v[8:9], v[154:155]
	v_pk_mul_f32 v[116:117], v[6:7], v[160:161]
	v_pk_mul_f32 v[114:115], v[4:5], v[158:159]
	v_pk_mul_f32 v[120:121], v[2:3], v[164:165]
	v_pk_mul_f32 v[118:119], v[0:1], v[162:163]
	v_pk_mul_f32 v[124:125], v[14:15], v[142:143]
	v_pk_mul_f32 v[122:123], v[12:13], v[140:141]
	v_pk_mul_f32 v[132:133], v[10:11], v[138:139]
	v_pk_mul_f32 v[130:131], v[8:9], v[136:137]
	v_pk_mul_f32 v[136:137], v[6:7], v[134:135]
	v_pk_mul_f32 v[134:135], v[4:5], v[166:167]
	v_pk_mul_f32 v[140:141], v[2:3], v[174:175]
	v_pk_mul_f32 v[138:139], v[0:1], v[170:171]
	v_pk_mul_f32 v[154:155], v[14:15], v[126:127]
	v_pk_mul_f32 v[152:153], v[12:13], v[176:177]
	v_pk_mul_f32 v[158:159], v[10:11], v[190:191]
	v_pk_mul_f32 v[156:157], v[8:9], v[178:179]
	v_pk_mul_f32 v[162:163], v[6:7], v[194:195]
	v_pk_mul_f32 v[160:161], v[4:5], v[192:193]
	global_store_dwordx4 v[148:149], v[52:55], off
	global_store_dwordx4 v[148:149], v[56:59], off offset:64
	global_store_dwordx4 v[148:149], v[114:117], off offset:512
	global_store_dwordx4 v[148:149], v[118:121], off offset:576
	global_store_dwordx4 v[150:151], v[122:125], off
	global_store_dwordx4 v[150:151], v[130:133], off offset:64
	global_store_dwordx4 v[150:151], v[134:137], off offset:512
	global_store_dwordx4 v[150:151], v[138:141], off offset:576
	global_store_dwordx4 v[168:169], v[152:155], off
	global_store_dwordx4 v[168:169], v[156:159], off offset:64
	global_store_dwordx4 v[168:169], v[160:163], off offset:512
	v_cndmask_b32_e32 v52, v62, v63, vcc
	v_rsq_f32_e32 v56, v52
	v_pk_mul_f32 v[54:55], v[2:3], v[198:199]
	v_pk_mul_f32 v[52:53], v[0:1], v[172:173]
	global_store_dwordx4 v[168:169], v[52:55], off offset:576
	s_mov_b64 s[0:1], 0x120000
	s_waitcnt vmcnt(12)
;     __device__ __forceinline__ void operator()(f32x4 (&acc)[2][2][4][2], const Unit& u, int wr, int wc, int fr, int fq) const {
;     ...
;         float rs[2][4];
; #pragma unroll
;         for (int ai = 0; ai < 2; ++ai)
; #pragma unroll
;             for (int m = 0; m < 4; ++m) rs[ai][m] = __hip_atomic_load(rowsq + row0 + ai * 128 + m * 16, __ATOMIC_RELAXED, __HIP_MEMORY_SCOPE_AGENT);
; #pragma unroll
;         for (int ai = 0; ai < 2; ++ai)
; #pragma unroll
;             for (int m = 0; m < 4; ++m) {
;                 const int row = row0 + ai * 128 + m * 16;
;                 const float rstd = rsqrtf(rs[ai][m] * (1.0f / D) + RMS_EPS);
; #pragma unroll
;                 for (int bj = 0; bj < 2; ++bj)
; #pragma unroll
;                     for (int n = 0; n < 2; ++n) { const int c = col0 + bj * 128 + n * 16; *(f32x4*)(out + (size_t)row * D + c) = acc[ai][bj][m][n] * rstd * gg[bj][n]; }
;             }
	v_pk_fma_f32 v[38:39], v[38:39], s[8:9], v[42:43] op_sel_hi:[1,0,0]
	v_mul_f32_e32 v52, 0x45800000, v56
	v_cndmask_b32_e32 v56, v56, v52, vcc
	v_pk_mul_f32 v[52:53], v[108:109], v[56:57] op_sel_hi:[1,0]
	v_pk_mul_f32 v[54:55], v[110:111], v[56:57] op_sel_hi:[1,0]
	v_pk_mul_f32 v[52:53], v[12:13], v[52:53]
	v_pk_mul_f32 v[54:55], v[14:15], v[54:55]
	global_store_dwordx4 v[128:129], v[52:55], off
	s_nop 1
	v_pk_mul_f32 v[52:53], v[104:105], v[56:57] op_sel_hi:[1,0]
	v_pk_mul_f32 v[54:55], v[106:107], v[56:57] op_sel_hi:[1,0]
	v_pk_mul_f32 v[52:53], v[8:9], v[52:53]
	v_pk_mul_f32 v[54:55], v[10:11], v[54:55]
	global_store_dwordx4 v[128:129], v[52:55], off offset:64
	s_nop 1
	v_pk_mul_f32 v[52:53], v[100:101], v[56:57] op_sel_hi:[1,0]
	v_pk_mul_f32 v[54:55], v[102:103], v[56:57] op_sel_hi:[1,0]
	v_pk_mul_f32 v[52:53], v[4:5], v[52:53]
	v_pk_mul_f32 v[54:55], v[6:7], v[54:55]
	global_store_dwordx4 v[128:129], v[52:55], off offset:512
	s_nop 1
	v_pk_mul_f32 v[54:55], v[96:97], v[56:57] op_sel_hi:[1,0]
	v_pk_mul_f32 v[52:53], v[98:99], v[56:57] op_sel_hi:[1,0]
	v_pk_fma_f32 v[56:57], v[50:51], s[8:9], v[42:43] op_sel_hi:[1,0,0]
	v_pk_mul_f32 v[52:53], v[2:3], v[52:53]
	v_mul_f32_e32 v50, 0x4b800000, v57
	v_cmp_gt_f32_e32 vcc, s4, v57
	v_mul_f32_e32 v42, 0x4b800000, v39
	s_nop 0
	v_cndmask_b32_e32 v50, v57, v50, vcc
	v_rsq_f32_e32 v57, v50
	v_pk_mul_f32 v[50:51], v[0:1], v[54:55]
	global_store_dwordx4 v[128:129], v[50:53], off offset:576
	s_nop 1
	v_mul_f32_e32 v50, 0x45800000, v57
	v_cndmask_b32_e32 v54, v57, v50, vcc
	v_pk_mul_f32 v[50:51], v[92:93], v[54:55] op_sel_hi:[1,0]
	v_pk_mul_f32 v[52:53], v[94:95], v[54:55] op_sel_hi:[1,0]
	v_pk_mul_f32 v[50:51], v[12:13], v[50:51]
	v_pk_mul_f32 v[52:53], v[14:15], v[52:53]
	global_store_dwordx4 v[112:113], v[50:53], off
	v_cmp_gt_f32_e32 vcc, s4, v56
	s_nop 0
	v_pk_mul_f32 v[50:51], v[88:89], v[54:55] op_sel_hi:[1,0]
	v_pk_mul_f32 v[52:53], v[90:91], v[54:55] op_sel_hi:[1,0]
	v_pk_mul_f32 v[50:51], v[8:9], v[50:51]
	v_pk_mul_f32 v[52:53], v[10:11], v[52:53]
	global_store_dwordx4 v[112:113], v[50:53], off offset:64
	s_nop 1
	v_pk_mul_f32 v[50:51], v[84:85], v[54:55] op_sel_hi:[1,0]
	v_pk_mul_f32 v[52:53], v[86:87], v[54:55] op_sel_hi:[1,0]
	v_pk_mul_f32 v[50:51], v[4:5], v[50:51]
	v_pk_mul_f32 v[52:53], v[6:7], v[52:53]
	global_store_dwordx4 v[112:113], v[50:53], off offset:512
	s_nop 1
	v_pk_mul_f32 v[50:51], v[80:81], v[54:55] op_sel_hi:[1,0]
	v_pk_mul_f32 v[52:53], v[82:83], v[54:55] op_sel_hi:[1,0]
	v_mul_f32_e32 v54, 0x4b800000, v56
	v_cndmask_b32_e32 v54, v56, v54, vcc
	v_rsq_f32_e32 v54, v54
	v_pk_mul_f32 v[52:53], v[2:3], v[52:53]
	v_pk_mul_f32 v[50:51], v[0:1], v[50:51]
	global_store_dwordx4 v[112:113], v[50:53], off offset:576
	v_lshl_add_u64 v[56:57], v[144:145], 2, v[146:147]
	v_lshl_add_u64 v[58:59], v[56:57], 0, s[0:1]
	v_mul_f32_e32 v50, 0x45800000, v54
	v_cndmask_b32_e32 v54, v54, v50, vcc
	s_mov_b32 s0, 0x120000
	v_pk_mul_f32 v[50:51], v[76:77], v[54:55] op_sel_hi:[1,0]
	v_pk_mul_f32 v[52:53], v[78:79], v[54:55] op_sel_hi:[1,0]
	v_add_co_u32_e32 v62, vcc, s0, v56
	v_pk_mul_f32 v[52:53], v[14:15], v[52:53]
	v_pk_mul_f32 v[50:51], v[12:13], v[50:51]
	v_addc_co_u32_e32 v63, vcc, 0, v57, vcc
	global_store_dwordx4 v[62:63], v[50:53], off
	v_cmp_gt_f32_e32 vcc, s4, v39
	s_mov_b64 s[0:1], 0x140000
	v_pk_mul_f32 v[50:51], v[72:73], v[54:55] op_sel_hi:[1,0]
	v_pk_mul_f32 v[52:53], v[74:75], v[54:55] op_sel_hi:[1,0]
	v_pk_mul_f32 v[50:51], v[8:9], v[50:51]
	v_pk_mul_f32 v[52:53], v[10:11], v[52:53]
	v_cndmask_b32_e32 v39, v39, v42, vcc
	global_store_dwordx4 v[58:59], v[50:53], off offset:64
	v_rsq_f32_e32 v39, v39
	v_lshl_add_u64 v[42:43], v[56:57], 0, s[0:1]
	v_pk_mul_f32 v[50:51], v[68:69], v[54:55] op_sel_hi:[1,0]
	v_pk_mul_f32 v[52:53], v[70:71], v[54:55] op_sel_hi:[1,0]
	v_pk_mul_f32 v[50:51], v[4:5], v[50:51]
	v_pk_mul_f32 v[52:53], v[6:7], v[52:53]
	global_store_dwordx4 v[58:59], v[50:53], off offset:512
	s_mov_b32 s0, 0x140000
	s_nop 0
	v_pk_mul_f32 v[50:51], v[64:65], v[54:55] op_sel_hi:[1,0]
	v_pk_mul_f32 v[52:53], v[66:67], v[54:55] op_sel_hi:[1,0]
	v_pk_mul_f32 v[50:51], v[0:1], v[50:51]
	v_pk_mul_f32 v[52:53], v[2:3], v[52:53]
	global_store_dwordx4 v[58:59], v[50:53], off offset:576
	s_nop 1
	v_mul_f32_e32 v50, 0x45800000, v39
	v_cndmask_b32_e32 v54, v39, v50, vcc
	v_pk_mul_f32 v[24:25], v[24:25], v[54:55] op_sel_hi:[1,0]
	v_pk_mul_f32 v[26:27], v[26:27], v[54:55] op_sel_hi:[1,0]
	v_pk_mul_f32 v[30:31], v[30:31], v[54:55] op_sel_hi:[1,0]
	v_pk_mul_f32 v[26:27], v[10:11], v[26:27]
	v_pk_mul_f32 v[24:25], v[8:9], v[24:25]
	v_pk_mul_f32 v[52:53], v[14:15], v[30:31]
	v_add_co_u32_e32 v30, vcc, s0, v56
	global_store_dwordx4 v[42:43], v[24:27], off offset:64
	v_pk_mul_f32 v[22:23], v[22:23], v[54:55] op_sel_hi:[1,0]
	v_addc_co_u32_e32 v31, vcc, 0, v57, vcc
	v_pk_mul_f32 v[26:27], v[28:29], v[54:55] op_sel_hi:[1,0]
	v_pk_mul_f32 v[24:25], v[6:7], v[22:23]
	v_pk_mul_f32 v[22:23], v[4:5], v[26:27]
	global_store_dwordx4 v[42:43], v[22:25], off offset:512
	v_cmp_gt_f32_e32 vcc, s4, v38
	v_pk_mul_f32 v[20:21], v[20:21], v[54:55] op_sel_hi:[1,0]
	v_mul_f32_e32 v22, 0x4b800000, v38
	v_cndmask_b32_e32 v22, v38, v22, vcc
	v_rsq_f32_e32 v26, v22
	v_pk_mul_f32 v[24:25], v[48:49], v[54:55] op_sel_hi:[1,0]
	v_pk_mul_f32 v[22:23], v[2:3], v[20:21]
	v_pk_mul_f32 v[20:21], v[0:1], v[24:25]
	global_store_dwordx4 v[42:43], v[20:23], off offset:576
	v_pk_mul_f32 v[50:51], v[60:61], v[54:55] op_sel_hi:[1,0]
	s_mov_b64 s[0:1], 0x160000
	v_mul_f32_e32 v20, 0x45800000, v26
	v_cndmask_b32_e32 v20, v26, v20, vcc
	v_pk_mul_f32 v[22:23], v[44:45], v[20:21] op_sel_hi:[1,0]
	v_pk_mul_f32 v[50:51], v[12:13], v[50:51]
	v_pk_mul_f32 v[24:25], v[46:47], v[20:21] op_sel_hi:[1,0]
	v_pk_mul_f32 v[12:13], v[12:13], v[22:23]
	v_lshl_add_u64 v[22:23], v[56:57], 0, s[0:1]
	s_mov_b32 s0, 0x160000
	v_pk_mul_f32 v[14:15], v[14:15], v[24:25]
	v_add_co_u32_e32 v24, vcc, s0, v56
	global_store_dwordx4 v[30:31], v[50:53], off
	s_nop 0
	v_addc_co_u32_e32 v25, vcc, 0, v57, vcc
	global_store_dwordx4 v[24:25], v[12:15], off
	s_nop 1
	v_pk_mul_f32 v[12:13], v[40:41], v[20:21] op_sel_hi:[1,0]
	v_pk_mul_f32 v[14:15], v[16:17], v[20:21] op_sel_hi:[1,0]
	v_pk_mul_f32 v[8:9], v[8:9], v[12:13]
	v_pk_mul_f32 v[10:11], v[10:11], v[14:15]
	global_store_dwordx4 v[22:23], v[8:11], off offset:64
	s_nop 1
	v_pk_mul_f32 v[8:9], v[36:37], v[20:21] op_sel_hi:[1,0]
	v_pk_mul_f32 v[10:11], v[18:19], v[20:21] op_sel_hi:[1,0]
	v_pk_mul_f32 v[4:5], v[4:5], v[8:9]
	v_pk_mul_f32 v[6:7], v[6:7], v[10:11]
	global_store_dwordx4 v[22:23], v[4:7], off offset:512
	s_nop 1
	v_pk_mul_f32 v[4:5], v[32:33], v[20:21] op_sel_hi:[1,0]
	v_pk_mul_f32 v[6:7], v[34:35], v[20:21] op_sel_hi:[1,0]
	v_pk_mul_f32 v[0:1], v[0:1], v[4:5]
	v_pk_mul_f32 v[2:3], v[2:3], v[6:7]
	global_store_dwordx4 v[22:23], v[0:3], off offset:576

; __device__ __forceinline__ unsigned xb_ld(unsigned* p)              { return __hip_atomic_load(p, __ATOMIC_RELAXED, __HIP_MEMORY_SCOPE_AGENT); }
; __device__ __forceinline__ unsigned xb_add(unsigned* p, unsigned v) { return __hip_atomic_fetch_add(p, v, __ATOMIC_RELAXED, __HIP_MEMORY_SCOPE_AGENT); }
; #define XB_SPIN(cond, bar) do { unsigned _sp = 0; while (cond) { __builtin_amdgcn_s_sleep(1); \
;     if ((++_sp & 255u) == 0u) { if (xb_ld(&(bar)[XB_TMO])) break; if (_sp > XB_SPIN_CAP) { atomicAdd(&(bar)[XB_TMO], 1u); break; } } } } while (0)
; __device__ __forceinline__ void xcd_barrier(const XcdBarrier& b) {
;     ...
;     if (threadIdx.x == 0) {
;         unsigned* bar = b.bar;
;         __builtin_amdgcn_s_waitcnt(0);
;         unsigned nloc = b.st[0], nx = b.st[1];
;         if (nloc == 0u) { xcd_barrier_complete(bar, b.x, nloc, nx); b.st[0] = nloc; b.st[1] = nx; }
;         const unsigned old = xb_add(&bar[XB_XSUB(b.x)], 1u);
;         const unsigned gen = old / nloc;
;         if (old + 1u == (gen + 1u) * nloc) {
;             __builtin_amdgcn_fence(__ATOMIC_RELEASE, "agent");
;             asm volatile("s_waitcnt vmcnt(0)" ::: "memory");
;             const unsigned og = xb_add(&bar[XB_TOP], 1u);
;             const unsigned tg = og / nx;
;             if (og + 1u == (tg + 1u) * nx) xb_add(&bar[XB_TOPGEN], 1u);
;             else XB_SPIN(xb_ld(&bar[XB_TOPGEN]) == tg, bar);
.LBB0_1383:
	s_or_b64 exec, exec, s[8:9]
	v_cvt_f32_u32_e32 v4, v2
	s_waitcnt vmcnt(0)
	buffer_inv sc1
	v_readfirstlane_b32 s6, v3
	v_sub_u32_e32 v3, 0, v2
	v_rcp_iflag_f32_e32 v4, v4
	v_add_u32_e32 v5, s6, v1
	v_mul_f32_e32 v4, 0x4f7ffffe, v4
	v_cvt_u32_f32_e32 v4, v4
	v_mul_lo_u32 v1, v3, v4
	v_mul_hi_u32 v1, v4, v1
	v_add_u32_e32 v1, v4, v1
	v_mul_hi_u32 v1, v5, v1
	v_mul_lo_u32 v3, v1, v2
	v_sub_u32_e32 v3, v5, v3
	v_add_u32_e32 v4, 1, v1
	v_cmp_ge_u32_e32 vcc, v3, v2
	s_nop 1
	v_cndmask_b32_e32 v1, v1, v4, vcc
	v_sub_u32_e32 v4, v3, v2
	v_cndmask_b32_e32 v3, v3, v4, vcc
	v_add_u32_e32 v4, 1, v1
	v_cmp_ge_u32_e32 vcc, v3, v2
	v_add_u32_e32 v3, 1, v5
	s_nop 0
	v_cndmask_b32_e32 v1, v1, v4, vcc
	v_mul_lo_u32 v4, v2, v1
	v_add_u32_e32 v2, v4, v2
	v_cmp_ne_u32_e32 vcc, v3, v2
	s_and_saveexec_b64 s[6:7], vcc
	s_xor_b64 s[6:7], exec, s[6:7]
	s_cbranch_execz .LBB0_1397
	s_waitcnt lgkmcnt(0)
	v_mov_b32_e32 v0, 0x2000
	global_load_dword v0, v0, s[4:5] offset:1024 sc1
	s_add_u32 s12, s4, 0x2400
	s_addc_u32 s13, s5, 0
	s_waitcnt vmcnt(0)
	v_cmp_eq_u32_e32 vcc, v0, v1
	s_and_saveexec_b64 s[8:9], vcc
	s_cbranch_execz .LBB0_1396
	s_add_u32 s10, s90, 0x10bd2a00
	s_addc_u32 s11, s91, 0
	s_mov_b32 s24, 1
	s_mov_b64 s[14:15], 0
	v_mov_b32_e32 v0, 0
	s_branch .LBB0_1387

; __device__ __forceinline__ unsigned xb_ld(unsigned* p)              { return __hip_atomic_load(p, __ATOMIC_RELAXED, __HIP_MEMORY_SCOPE_AGENT); }
; #define XB_SPIN(cond, bar) do { unsigned _sp = 0; while (cond) { __builtin_amdgcn_s_sleep(1); \
;     if ((++_sp & 255u) == 0u) { if (xb_ld(&(bar)[XB_TMO])) break; if (_sp > XB_SPIN_CAP) { atomicAdd(&(bar)[XB_TMO], 1u); break; } } } } while (0)
; __device__ __forceinline__ void xcd_barrier(const XcdBarrier& b) {
;     ...
;         } else {
;             XB_SPIN(xb_ld(&bar[XB_XGEN(b.x)]) == gen, bar);
;             __builtin_amdgcn_fence(__ATOMIC_ACQUIRE, "agent");
;             asm volatile("s_waitcnt vmcnt(0)" ::: "memory");
;         }
.LBB0_1396:
	s_or_b64 exec, exec, s[8:9]
	s_waitcnt vmcnt(0)
	s_waitcnt vmcnt(0)

; __device__ __forceinline__ unsigned xb_ld(unsigned* p)              { return __hip_atomic_load(p, __ATOMIC_RELAXED, __HIP_MEMORY_SCOPE_AGENT); }
; __device__ __forceinline__ unsigned xb_add(unsigned* p, unsigned v) { return __hip_atomic_fetch_add(p, v, __ATOMIC_RELAXED, __HIP_MEMORY_SCOPE_AGENT); }
; #define XB_SPIN(cond, bar) do { unsigned _sp = 0; while (cond) { __builtin_amdgcn_s_sleep(1); \
;     if ((++_sp & 255u) == 0u) { if (xb_ld(&(bar)[XB_TMO])) break; if (_sp > XB_SPIN_CAP) { atomicAdd(&(bar)[XB_TMO], 1u); break; } } } } while (0)
; __device__ __forceinline__ void xcd_barrier(const XcdBarrier& b) {
;     ...
;             const unsigned og = xb_add(&bar[XB_TOP], 1u);
;             const unsigned tg = og / nx;
;             if (og + 1u == (tg + 1u) * nx) xb_add(&bar[XB_TOPGEN], 1u);
;             else XB_SPIN(xb_ld(&bar[XB_TOPGEN]) == tg, bar);
;             __builtin_amdgcn_fence(__ATOMIC_ACQUIRE, "agent");
;             xb_add(&bar[XB_XGEN(b.x)], 1u);
.LBB0_1414:
	s_or_b64 exec, exec, s[6:7]
	s_mov_b64 s[6:7], exec
	v_mbcnt_lo_u32_b32 v0, s6, 0
	v_mbcnt_hi_u32_b32 v0, s7, v0
	v_cmp_eq_u32_e32 vcc, 0, v0
	s_waitcnt vmcnt(0)
	s_and_saveexec_b64 s[8:9], vcc
	s_cbranch_execz .LBB0_1416
	s_bcnt1_i32_b64 s6, s[6:7]
	v_mov_b32_e32 v0, 0x2000
	v_mov_b32_e32 v1, s6
	global_atomic_add v0, v1, s[4:5] offset:1024
